# C item setup waits only for its first K/V stage before the step loop (as A and B already do)
# speedup vs baseline: 1.0041x; 1.0012x over previous
; #define LAS __attribute__((address_space(3)))
; #define WAITBAR2() asm volatile("s_waitcnt vmcnt(2) lgkmcnt(0)\n\ts_barrier" ::: "memory")
; __device__ __forceinline__ Stage make_stage(int tid, const bf16_t* QK, const bf16_t* VT, size_t tok0, int kcol, int vrow) {
;     Stage st; const int w = __builtin_amdgcn_readfirstlane(tid >> 6), l = tid & 63, h = l >> 5, r5 = l & 31, pr = (r5 & ~12) | ((r5 & 4) << 1) | ((r5 & 8) >> 1), u = w >> 2;
;     st.ksrc = QK + (tok0 + 32 * u + pr) * 2048 + kcol + 16 * (w & 3) + 8 * h; st.kdst = (unsigned)(u * 8192 + (w & 3) * 1024);
;     st.vsrc = VT + (size_t)(vrow + 32 * ((w >> 1) & 1) + r5) * MTOK + tok0 + 32 * u + 16 * (w & 1) + 8 * h; st.vdst = (unsigned)(u * 8192 + 4096 + (w & 3) * 1024);
;     return st;
; }
; __device__ __forceinline__ void blk_C(int b, int hd, int chunk, const bf16_t* QK, const bf16_t* VT, bf16_t* mixed, LAS unsigned char* lds, int tid, int lane, int wave) {
;     const int q = lane & 31, h = lane >> 5, qb = chunk * 8 + wave;
;     const size_t tok0 = (size_t)b * SEQ;
;     const bf16_t* Qp = QK + (tok0 + qb * 32 + q) * 2048 + 1536 + hd * 64 + 8 * h;
;     bf16x8 qf[4];
; #pragma unroll
;     for (int s = 0; s < 4; ++s) qf[s] = *(const bf16x8*)(Qp + 16 * s);
;     const Stage st = make_stage(tid, QK, VT, tok0, 1792 + hd * 64, 768 + hd * 64);
;     LAS unsigned char* sb = lds + SBUF_OFF; volatile LAS unsigned* flags = (volatile LAS unsigned*)(lds + ITEM_OFF) + 16;
;     const int sb_end = chunk * 4 + 3;
;     int s_iss = sb_end, slot_i = 0, slot_c = 0;
;     ...
;     ISSUE_DN(); ISSUE_DN();
;     WAITBAR2();
;     f32x16 o0 = {}, o1 = {}; float carry = 0.f; bool done = false;
.LBB0_318:
	s_or_b64 exec, exec, s[0:1]
	s_cmpk_gt_i32 s28, 0x3ff
	s_mov_b64 s[0:1], -1
	s_cbranch_scc0 .LBB0_332
	s_cmpk_gt_u32 s28, 0x7ff
	s_cbranch_scc0 .LBB0_383
	s_add_i32 s0, s28, 0xfffff800
	s_lshr_b32 s18, s0, 5
	s_sub_i32 s19, 31, s18
	s_lshl_b32 s29, s19, 3
	s_add_i32 s29, s29, s25
	s_lshl_b32 s0, s28, 11
	s_and_b32 s27, s0, 0xe000
	s_lshl_b32 s0, s29, 5
	s_ashr_i32 s1, s0, 31
	s_add_u32 s0, s0, s27
	s_addc_u32 s1, s1, 0
	v_mov_b32_e32 v81, s1
	v_or_b32_e32 v80, s0, v172
	s_lshl_b32 s0, s28, 6
	v_lshlrev_b64 v[2:3], 12, v[80:81]
	s_and_b32 s30, s0, 0xc0
	v_readfirstlane_b32 s31, v170
	v_lshl_add_u64 v[2:3], s[80:81], 0, v[2:3]
	s_lshl_b32 s92, s30, 1
	s_ashr_i32 s35, s31, 8
	v_lshl_add_u64 v[2:3], v[2:3], 0, s[92:93]
	v_lshlrev_b32_e32 v0, 1, v174
	s_lshl_b32 s0, s35, 5
	v_lshl_add_u64 v[2:3], v[2:3], 0, v[0:1]
	s_ashr_i32 s1, s0, 31
	v_or_b32_e32 v0, s27, v177
	global_load_dwordx4 v[64:67], v[2:3], off offset:3072
	global_load_dwordx4 v[68:71], v[2:3], off offset:3104
	global_load_dwordx4 v[72:75], v[2:3], off offset:3136
	global_load_dwordx4 v[76:79], v[2:3], off offset:3168
	v_lshl_add_u64 v[2:3], s[0:1], 0, v[0:1]
	s_ashr_i32 s34, s31, 6
	v_lshlrev_b64 v[2:3], 12, v[2:3]
	v_lshl_add_u64 v[2:3], s[80:81], 0, v[2:3]
	s_and_b32 s52, s34, 3
	v_lshl_add_u64 v[2:3], v[2:3], 0, s[92:93]
	s_lshl_b32 s92, s52, 5
	v_lshl_add_u64 v[2:3], v[2:3], 0, s[92:93]
	v_lshlrev_b32_e32 v0, 1, v176
	s_lshr_b32 s31, s31, 2
	v_lshl_add_u64 v[82:83], v[2:3], 0, v[0:1]
	v_and_or_b32 v2, s31, 32, v172
	v_or_b32_e32 v2, s30, v2
	v_lshlrev_b32_e32 v2, 17, v2
	v_mov_b32_e32 v3, v1
	v_lshl_add_u64 v[2:3], s[4:5], 0, v[2:3]
	s_lshl_b32 s92, s27, 1
	v_lshl_add_u64 v[2:3], v[2:3], 0, s[92:93]
	v_lshl_add_u64 v[2:3], s[0:1], 1, v[2:3]
	s_lshl_b32 s0, s34, 5
	s_and_b32 s92, s0, 32
	v_lshl_add_u64 v[2:3], v[2:3], 0, s[92:93]
	v_lshl_add_u64 v[2:3], v[2:3], 0, v[0:1]
	s_mov_b64 s[0:1], 0x6000000
	v_lshl_add_u64 v[84:85], v[2:3], 0, s[0:1]
	s_lshl_b32 s0, s19, 2
	s_lshl_b32 s35, s35, 13
	s_lshl_b32 s52, s52, 10
	s_or_b32 s31, s0, 3
	s_or_b32 s35, s52, s35
	s_lshl_b32 s92, s31, 18
	v_lshl_add_u64 v[2:3], v[82:83], 0, s[92:93]
	s_add_i32 s34, s35, 0
	v_lshl_add_u64 v[2:3], v[2:3], 0, s[10:11]
	s_add_i32 m0, s34, 0x8900
	s_lshl_b32 s92, s31, 7
	s_or_b32 s0, s0, 2
	global_load_lds_dwordx4 v[2:3], off
	v_lshl_add_u64 v[2:3], v[84:85], 0, s[92:93]
	s_add_i32 m0, s34, 0x9900
	s_lshl_b32 s92, s0, 18
	global_load_lds_dwordx4 v[2:3], off
	v_lshl_add_u64 v[2:3], v[82:83], 0, s[92:93]
	v_lshl_add_u64 v[2:3], v[2:3], 0, s[10:11]
	s_add_i32 m0, s34, 0xc900
	s_lshl_b32 s92, s0, 7
	global_load_lds_dwordx4 v[2:3], off
	v_lshl_add_u64 v[2:3], v[84:85], 0, s[92:93]
	s_add_i32 m0, s34, 0xd900
	v_mov_b32_e32 v14, v1
	global_load_lds_dwordx4 v[2:3], off
	s_waitcnt vmcnt(2) lgkmcnt(0)
	s_barrier
	v_mov_b32_e32 v15, v1
	s_lshl_b32 s0, s18, 3
	v_mov_b32_e32 v0, v1
	v_mov_b32_e32 v2, v1
	v_mov_b32_e32 v3, v1
	v_mov_b32_e32 v4, v1
	v_mov_b32_e32 v5, v1
	v_mov_b32_e32 v6, v1
	v_mov_b32_e32 v7, v1
	v_mov_b32_e32 v8, v1
	v_mov_b32_e32 v9, v1
	v_mov_b32_e32 v10, v1
	v_mov_b32_e32 v11, v1
	v_mov_b32_e32 v12, v1
	v_mov_b32_e32 v13, v1
	v_mov_b64_e32 v[30:31], v[14:15]
	v_mov_b64_e32 v[46:47], v[14:15]
	s_mov_b32 s6, s95
	s_mov_b32 s35, 2
	s_sub_i32 s52, 0xfe, s0
	s_mov_b32 s53, 0
	s_mov_b64 s[0:1], 0
	v_mov_b32_e32 v86, 0
	s_mov_b64 s[18:19], 0
	s_mov_b32 s27, s94
	v_mov_b64_e32 v[28:29], v[12:13]
	v_mov_b64_e32 v[26:27], v[10:11]
	v_mov_b64_e32 v[24:25], v[8:9]
	v_mov_b64_e32 v[22:23], v[6:7]
	v_mov_b64_e32 v[20:21], v[4:5]
	v_mov_b64_e32 v[18:19], v[2:3]
	v_mov_b64_e32 v[16:17], v[0:1]
	v_mov_b64_e32 v[44:45], v[12:13]
	v_mov_b64_e32 v[42:43], v[10:11]
	v_mov_b64_e32 v[40:41], v[8:9]
	v_mov_b64_e32 v[38:39], v[6:7]
	v_mov_b64_e32 v[36:37], v[4:5]
	v_mov_b64_e32 v[34:35], v[2:3]
	v_mov_b64_e32 v[32:33], v[0:1]
	s_mov_b32 s95, 0
	s_waitcnt vmcnt(2)
	s_branch .LBB0_322
